# on top of v2: phase-3 W_in transpose (with norm-gain multiply): 8 weight-row loads + 8 gain loads in flight per trip with counted waits, instead of load-wait-gainload-wait per row
# speedup vs baseline: 1.0091x; 1.0091x over previous
; #define LAS __attribute__((address_space(3)))
; #define GAS __attribute__((address_space(1)))
; #define ARGP(i) ((const GAS float*)ldptr(ptab, (i)))
; __device__ __forceinline__ void transpose_item(const GAS float* W, int K, int N, const GAS float* gain, GAS bf16* WT, LAS float* scr, int item, int lane, int remap) {
;     ...
; #pragma unroll 8
;     for (int i = 0; i < 32; ++i) { const int kk = 2 * i + (lane >> 5); float w = W[(size_t)(k0 + kk) * N + ns + (lane & 31)]; if (gain) w *= gain[k0 + kk]; scr[kk * 33 + (lane & 31)] = w; }
; __global__ void __launch_bounds__(512, 2) fwd(Args a) {
;     ...
;                 const GAS float* w_in = (nev ? ARGP(2) : ARGP(9)) + (size_t)nj * D * PW; const GAS float* ln = (nev ? ARGP(1) : ARGP(8)) + (size_t)nj * D;
;                 LAS float* scr = (LAS float*)((LAS unsigned char*)lds + c.wave * 16384);
;                 for (int it = c.gw; it < (D / 64) * (PW / 32); it += c.ngw) transpose_item(w_in, D, PW, ln, c.Wt_in, scr, it, c.lane, nev);
.LBB0_654:
	s_andn2_b64 vcc, exec, s[10:11]
	s_cbranch_vccnz .Lmy_win3_nogain
	v_lshl_add_u64 v[42:43], s[16:17], 0, v[24:25]
	v_lshl_add_u64 v[26:27], s[16:17], 0, v[8:9]
	global_load_dword v52, v[42:43], off
	v_lshl_add_u64 v[42:43], v[22:23], 0, s[14:15]
	global_load_dword v44, v[42:43], off
	v_lshl_add_u64 v[42:43], v[20:21], 0, s[14:15]
	global_load_dword v45, v[42:43], off
	v_lshl_add_u64 v[42:43], v[18:19], 0, s[14:15]
	global_load_dword v46, v[42:43], off
	v_lshl_add_u64 v[42:43], v[16:17], 0, s[14:15]
	global_load_dword v47, v[42:43], off
	v_lshl_add_u64 v[42:43], v[14:15], 0, s[14:15]
	global_load_dword v48, v[42:43], off
	v_lshl_add_u64 v[42:43], v[12:13], 0, s[14:15]
	global_load_dword v49, v[42:43], off
	v_lshl_add_u64 v[42:43], v[10:11], 0, s[14:15]
	global_load_dword v50, v[42:43], off
	v_lshl_add_u64 v[42:43], v[6:7], 0, s[14:15]
	global_load_dword v51, v[42:43], off
	global_load_dword v53, v[26:27], off offset:8
	global_load_dword v54, v[26:27], off offset:16
	global_load_dword v55, v[26:27], off offset:24
	global_load_dword v56, v[26:27], off offset:32
	global_load_dword v57, v[26:27], off offset:40
	global_load_dword v58, v[26:27], off offset:48
	global_load_dword v59, v[26:27], off offset:56
	s_waitcnt vmcnt(14)
	v_mul_f32_e32 v44, v44, v52
	ds_write_b32 v40, v44
	s_waitcnt vmcnt(6)
	v_mul_f32_e32 v45, v45, v53
	ds_write_b32 v40, v45 offset:264
	s_waitcnt vmcnt(5)
	v_mul_f32_e32 v46, v46, v54
	ds_write_b32 v40, v46 offset:528
	s_waitcnt vmcnt(4)
	v_mul_f32_e32 v47, v47, v55
	ds_write_b32 v40, v47 offset:792
	s_waitcnt vmcnt(3)
	v_mul_f32_e32 v48, v48, v56
	ds_write_b32 v40, v48 offset:1056
	s_waitcnt vmcnt(2)
	v_mul_f32_e32 v49, v49, v57
	ds_write_b32 v40, v49 offset:1320
	s_waitcnt vmcnt(1)
	v_mul_f32_e32 v50, v50, v58
	ds_write_b32 v40, v50 offset:1584
	s_waitcnt vmcnt(0)
	v_mul_f32_e32 v41, v51, v59
	s_branch .LBB0_653
